# c25: in-proj tile schedule rotates the column tile by 5 per row group so every workgroup gets a mix of output types (epilogue costs) instead of one type
# speedup vs baseline: 1.0238x; 1.0033x over previous
; #define LDSAS __attribute__((address_space(3)))
; #define G_ISSUE(kt, st) do { G_ISSUE1(kt, st, 0); G_ISSUE1(kt, st, 1); G_ISSUE1(kt, st, 2); G_ISSUE1(kt, st, 3); } while (0)
; template <bool LOWREG = false>
; __device__ __forceinline__ void gemm_core(const bf16_t* __restrict__ A, int lda, const bf16_t* __restrict__ Bt, int ldb, int K, f32x4 (&acc)[8][4], unsigned char* smem, int tid) {
;     asm volatile("" : "+v"(tid));
;     const int lane = tid & 63, w = __builtin_amdgcn_readfirstlane(tid >> 6), wm = w >> 2, wn = w & 3, idx = lane & 15, kq = lane >> 4;
;     unsigned offA[4], offB[4];
; #pragma unroll
;     for (int j = 0; j < 4; ++j) { const int row = (j * 8 + w) * 8 + (lane >> 3), c = (lane & 7) ^ ((row >> 1) & 7);
;         offA[j] = (unsigned)(row * lda + c * 8) * 2u; offB[j] = (unsigned)(row * ldb + c * 8) * 2u; }
; #pragma unroll
;     for (int mi = 0; mi < 8; ++mi)
; #pragma unroll
;         for (int ni = 0; ni < 4; ++ni) acc[mi][ni] = (f32x4){0.f, 0.f, 0.f, 0.f};
;     LDSAS unsigned char* lds = (LDSAS unsigned char*)smem;
;     ...
;     const int nk = K >> 6;
;     G_ISSUE(0, 0);
;     asm volatile("s_waitcnt vmcnt(0)" ::: "memory");
;     __syncthreads();
;     const int swz = (idx >> 1) & 7;
;     const int aoff = (wm * 128 + idx) * 128, boff = G_AB + (wn * 64 + idx) * 128;
; __device__ void gemm1_phase(const Params& p, int l, int hb, unsigned char* smem) {
;     ...
;     for (int t = blockIdx.x; t < NTILES; t += gridDim.x) {
;         const int grp = t / GRP, r = t % GRP, jx = NT * (r & 7) + (r >> 3), mt = grp * 8 + (jx & 7), nt = jx >> 3;
;         const int m0 = mt * 256, n0 = nt * 256;
.Lg1_nosplit:
	s_mul_hi_i32 s9, s99, 0x78787879
	s_lshr_b32 s11, s9, 31
	s_ashr_i32 s9, s9, 7
	s_add_i32 s9, s9, s11
	s_mul_i32 s11, s9, 0x110
	s_sub_i32 s11, s99, s11
	s_and_b32 s12, s11, 7
	s_mul_i32 s12, s12, 34
	s_ashr_i32 s11, s11, 3
	s_add_i32 s12, s12, s11
	s_lshl_b32 s11, s12, 8
	s_lshl_b32 s9, s9, 11
	s_and_b32 s11, s11, 0x700
	s_or_b32 s56, s11, s9
	s_lshr_b32 s36, s12, 3
	s_lshr_b32 s11, s9, 11
	s_mul_i32 s11, s11, 5
	s_add_i32 s36, s36, s11
	s_mul_i32 s11, s36, 1928
	s_lshr_b32 s11, s11, 16
	s_mul_i32 s11, s11, 34
	s_sub_i32 s36, s36, s11
	s_lshl_b32 s36, s36, 8
	s_mov_b32 s11, s36
	s_ashr_i32 s57, s56, 31
	s_lshl_b64 s[16:17], s[56:57], 11
	s_add_u32 s18, s92, s16
	s_addc_u32 s19, s93, s17
	s_ashr_i32 s37, s36, 31
	s_lshl_b64 s[20:21], s[36:37], 11
	v_mov_b32_e32 v0, v210
	s_add_u32 s22, s94, s20
	s_addc_u32 s23, s95, s21
	v_readfirstlane_b32 s12, v0
	s_ashr_i32 s24, s12, 6
	s_and_b32 s101, s24, 3
	s_cmp_lg_u32 s101, 0
	s_cselect_b32 s101, 1, 2
	s_cmp_eq_u32 s36, 0x2100
	s_cselect_b32 s101, s101, 0
	s_lshr_b32 s98, s24, 2
	s_cmp_lg_u32 s98, s100
	s_cselect_b32 s98, 1, 0
	s_cmp_lt_i32 s100, 0
	s_cselect_b32 s98, 0, s98
	s_or_b32 s101, s101, s98
	v_bfe_u32 v2, v0, 3, 3
	v_lshl_or_b32 v3, s24, 3, v2
	v_lshrrev_b32_e32 v4, 1, v3
	v_xor_b32_e32 v4, v4, v0
	v_lshlrev_b32_e32 v4, 4, v4
	s_lshl_b32 s9, s24, 10
	v_and_b32_e32 v4, 0x70, v4
	s_add_i32 s9, s9, 0
	v_lshl_or_b32 v3, v3, 11, v4
	s_mov_b32 m0, s9
	v_add_u32_e32 v5, 0x20000, v3
	global_load_lds_dwordx4 v3, s[18:19]
	s_add_i32 m0, s9, 0x8000
	v_add_u32_e32 v6, 0x40000, v3
	global_load_lds_dwordx4 v3, s[22:23]
	s_add_i32 m0, s9, 0x2000
	v_add_u32_e32 v7, 0x60000, v3
	global_load_lds_dwordx4 v5, s[18:19]
	s_add_i32 m0, s9, 0xa000
	v_and_b32_e32 v1, 15, v0
	global_load_lds_dwordx4 v5, s[22:23]
	s_add_i32 m0, s9, 0x4000
	v_bfe_u32 v8, v0, 4, 2
	global_load_lds_dwordx4 v6, s[18:19]
	s_add_i32 m0, s9, 0xc000
	v_lshrrev_b32_e32 v3, 1, v0
	global_load_lds_dwordx4 v6, s[22:23]
	s_add_i32 m0, s9, 0x6000
	v_bfe_u32 v0, v0, 1, 3
	global_load_lds_dwordx4 v7, s[18:19]
	s_add_i32 m0, s9, 0xe000
	s_lshr_b32 s18, s12, 1
	global_load_lds_dwordx4 v7, s[22:23]
	s_and_b32 s18, s18, 0x1ffff80
	s_and_b32 s12, s12, 0xc0
	v_or_b32_e32 v5, s18, v1
	v_or_b32_e32 v1, s12, v1
	s_lshl_b32 s12, s24, 14
	s_add_u32 s16, s96, s16
	v_lshlrev_b32_e32 v149, 7, v5
	v_bitop3_b32 v0, v8, v0, 4 bitop3:0x36
	v_lshlrev_b32_e32 v5, 11, v2
	s_addc_u32 s17, s97, s17
	s_add_i32 s18, s12, 0x20000
	v_lshlrev_b32_e32 v147, 7, v1
	v_bitop3_b32 v1, v8, v3, 7 bitop3:0x78
	v_lshlrev_b32_e32 v146, 4, v0
	v_or3_b32 v80, s12, v5, v4
	v_or3_b32 v0, s18, v5, v4
	s_add_i32 s18, s12, 0x40000
	s_add_i32 s12, s12, 0x60000
	v_lshlrev_b32_e32 v148, 4, v1
	v_mov_b32_e32 v1, v81
	v_or3_b32 v2, s18, v5, v4
	v_mov_b32_e32 v3, v81
	v_or3_b32 v4, s12, v5, v4
	v_mov_b32_e32 v5, v81
	v_lshl_add_u64 v[130:131], s[16:17], 0, v[80:81]
	v_lshl_add_u64 v[132:133], s[16:17], 0, v[0:1]
	v_lshl_add_u64 v[134:135], s[16:17], 0, v[2:3]
	v_lshl_add_u64 v[136:137], s[16:17], 0, v[4:5]
	s_add_u32 s16, s64, s20
	s_waitcnt vmcnt(0)
	s_addc_u32 s17, s65, s21
	v_lshl_add_u64 v[140:141], s[16:17], 0, v[0:1]
	v_mov_b32_e32 v0, 0
	v_lshl_add_u64 v[138:139], s[16:17], 0, v[80:81]
	v_lshl_add_u64 v[142:143], s[16:17], 0, v[2:3]
	v_lshl_add_u64 v[144:145], s[16:17], 0, v[4:5]
	s_mov_b32 s12, 0
	s_mov_b64 s[38:39], 0
	v_mov_b32_e32 v1, v0
	v_mov_b32_e32 v2, v0
	v_mov_b32_e32 v3, v0
	v_mov_b32_e32 v4, v0
	v_mov_b32_e32 v5, v0
	v_mov_b32_e32 v6, v0
	v_mov_b32_e32 v7, v0
	v_mov_b32_e32 v8, v0
	v_mov_b32_e32 v9, v0
	s_waitcnt vmcnt(0)
	v_mov_b32_e32 v10, v0
	v_mov_b32_e32 v11, v0
	v_mov_b32_e32 v12, v0
	v_mov_b32_e32 v13, v0
	v_mov_b32_e32 v14, v0
	v_mov_b32_e32 v15, v0
	v_mov_b32_e32 v16, v0
	v_mov_b32_e32 v17, v0
	v_mov_b32_e32 v18, v0
	v_mov_b32_e32 v19, v0
	v_mov_b32_e32 v20, v0
	v_mov_b32_e32 v21, v0
	v_mov_b32_e32 v22, v0
	v_mov_b32_e32 v23, v0
	v_mov_b32_e32 v24, v0
	v_mov_b32_e32 v25, v0
	v_mov_b32_e32 v26, v0
	v_mov_b32_e32 v27, v0
	v_mov_b32_e32 v28, v0
	v_mov_b32_e32 v29, v0
	v_mov_b32_e32 v30, v0
	v_mov_b32_e32 v31, v0
	v_mov_b32_e32 v32, v0
	v_mov_b32_e32 v33, v0
	v_mov_b32_e32 v34, v0
	v_mov_b32_e32 v35, v0
	v_mov_b32_e32 v36, v0
	v_mov_b32_e32 v37, v0
	v_mov_b32_e32 v38, v0
	v_mov_b32_e32 v39, v0
	v_mov_b32_e32 v40, v0
	v_mov_b32_e32 v41, v0
	v_mov_b32_e32 v42, v0
	v_mov_b32_e32 v43, v0
	v_mov_b32_e32 v44, v0
	v_mov_b32_e32 v45, v0
	v_mov_b32_e32 v46, v0
	v_mov_b32_e32 v47, v0
	v_mov_b32_e32 v48, v0
	v_mov_b32_e32 v49, v0
	v_mov_b32_e32 v50, v0
	v_mov_b32_e32 v51, v0
	v_mov_b32_e32 v52, v0
	v_mov_b32_e32 v53, v0
	v_mov_b32_e32 v54, v0
	v_mov_b32_e32 v55, v0
	v_mov_b32_e32 v56, v0
	v_mov_b32_e32 v57, v0
	v_mov_b32_e32 v58, v0
	v_mov_b32_e32 v59, v0
	v_mov_b32_e32 v60, v0
	v_mov_b32_e32 v61, v0
	v_mov_b32_e32 v62, v0
	v_mov_b32_e32 v63, v0
	v_mov_b32_e32 v64, v0
	v_mov_b32_e32 v65, v0
	v_mov_b32_e32 v66, v0
	v_mov_b32_e32 v67, v0
	v_mov_b32_e32 v68, v0
	v_mov_b32_e32 v69, v0
	v_mov_b32_e32 v70, v0
	v_mov_b32_e32 v71, v0
	v_mov_b32_e32 v72, v0
	v_mov_b32_e32 v73, v0
	v_mov_b32_e32 v74, v0
	v_mov_b32_e32 v75, v0
	v_mov_b32_e32 v76, v0
	v_mov_b32_e32 v77, v0
	v_mov_b32_e32 v78, v0
	v_mov_b32_e32 v79, v0
	v_mov_b32_e32 v82, v0
	v_mov_b32_e32 v83, v0
	v_mov_b32_e32 v84, v0
	v_mov_b32_e32 v85, v0
	v_mov_b32_e32 v86, v0
	v_mov_b32_e32 v87, v0
	v_mov_b32_e32 v88, v0
	v_mov_b32_e32 v89, v0
	v_mov_b32_e32 v90, v0
	v_mov_b32_e32 v91, v0
	v_mov_b32_e32 v92, v0
	v_mov_b32_e32 v93, v0
	v_mov_b32_e32 v94, v0
	v_mov_b32_e32 v95, v0
	v_mov_b32_e32 v96, v0
	v_mov_b32_e32 v97, v0
	v_mov_b32_e32 v98, v0
	v_mov_b32_e32 v99, v0
	v_mov_b32_e32 v100, v0
	v_mov_b32_e32 v101, v0
	v_mov_b32_e32 v102, v0
	v_mov_b32_e32 v103, v0
	v_mov_b32_e32 v104, v0
	v_mov_b32_e32 v105, v0
	v_mov_b32_e32 v106, v0
	v_mov_b32_e32 v107, v0
	v_mov_b32_e32 v108, v0
	v_mov_b32_e32 v109, v0
	v_mov_b32_e32 v110, v0
	v_mov_b32_e32 v111, v0
	v_mov_b32_e32 v112, v0
	v_mov_b32_e32 v113, v0
	v_mov_b32_e32 v114, v0
	v_mov_b32_e32 v115, v0
	v_mov_b32_e32 v116, v0
	v_mov_b32_e32 v117, v0
	v_mov_b32_e32 v118, v0
	v_mov_b32_e32 v119, v0
	v_mov_b32_e32 v120, v0
	v_mov_b32_e32 v121, v0
	v_mov_b32_e32 v122, v0
	v_mov_b32_e32 v123, v0
	v_mov_b32_e32 v124, v0
	v_mov_b32_e32 v125, v0
	v_mov_b32_e32 v126, v0
	v_mov_b32_e32 v127, v0
	v_mov_b32_e32 v128, v0
	v_mov_b32_e32 v129, v0
	s_waitcnt lgkmcnt(0)
	s_barrier
